# layer-1 weight conversion split: w13 of layer 1 converted at the head of phase 8 by the workgroups that own a single GEMM unit there (10 us after the barrier), the rest stays at the head of phase 6
# speedup vs baseline: 1.0057x; 1.0057x over previous
.LBB0_22:
	s_cmp_eq_u32 s66, 11
	s_cbranch_scc0 .Lstg_n0
	s_cmp_ge_u32 s99, 128
	s_cbranch_scc0 .Lstg_end
	s_movk_i32 s98, 1200
	s_branch .Lstg_go
.Lstg_n0:
	s_cmp_eq_u32 s66, 1
	s_cbranch_scc0 .Lstg_n1
	s_cmp_ge_u32 s99, 192
	s_cbranch_scc0 .Lstg_end
	s_movk_i32 s98, 1200
	s_branch .Lstg_go

.Lwt1_loop:
	s_cmp_ge_u32 s16, 0x540
	s_cbranch_scc1 .Lwt1_done
	s_cmp_lt_u32 s16, 0x140
	s_cbranch_scc1 .Lwt1_d0
	s_cmp_lt_u32 s16, 0x180
	s_cbranch_scc1 .Lwt1_d1
	s_cmp_lt_u32 s16, 0x280
	s_cbranch_scc1 .Lwt1_d2
	s_branch .Lwt1_d3

.Lwt1_d3:
	s_sub_u32 s19, s16, 0x280
	s_mov_b32 s46, 0xa0
	s_mov_b32 s47, 0xb00000
	s_mov_b32 s48, 0x0
	s_mov_b32 s49, 0x0
	s_mov_b32 s50, 0x5200000
	s_mov_b32 s51, 0
	s_mov_b32 s26, 0x1000
	s_mov_b32 s39, 0x40000
	s_mov_b32 s27, 0x1600
	s_mov_b32 s28, 0x10
	s_mov_b32 s29, 0x10000000
	s_mov_b32 s30, 0
	s_mov_b32 s31, 0x0
	s_branch .Lwt1_common

.Lwt1_skip:
	s_cmp_eq_u32 s66, 8
	s_cbranch_scc0 .Lwt8_skip
	s_cmp_ge_u32 s99, 0x80
	s_cbranch_scc0 .Lwt8_skip
	s_load_dword vcc_lo, s[100:101], 0xc0
	s_waitcnt lgkmcnt(0)
	s_cmp_eq_u32 vcc_lo, 0x100
	s_cbranch_scc0 .Lwt8_skip
	s_mov_b64 exec, -1
	v_writelane_b32 v59, s16, 0
	v_writelane_b32 v59, s17, 1
	v_writelane_b32 v59, s18, 2
	v_writelane_b32 v59, s19, 3
	v_writelane_b32 v59, s20, 4
	v_writelane_b32 v59, s21, 5
	v_writelane_b32 v59, s22, 6
	v_writelane_b32 v59, s23, 7
	v_writelane_b32 v59, s24, 8
	v_writelane_b32 v59, s25, 9
	v_writelane_b32 v59, s26, 10
	v_writelane_b32 v59, s27, 11
	v_writelane_b32 v59, s28, 12
	v_writelane_b32 v59, s29, 13
	v_writelane_b32 v59, s30, 14
	v_writelane_b32 v59, s31, 15
	v_writelane_b32 v59, s32, 16
	v_writelane_b32 v59, s33, 17
	v_writelane_b32 v59, s34, 18
	v_writelane_b32 v59, s35, 19
	v_writelane_b32 v59, s36, 20
	v_writelane_b32 v59, s37, 21
	v_writelane_b32 v59, s38, 22
	v_writelane_b32 v59, s39, 23
	v_writelane_b32 v59, s40, 24
	v_writelane_b32 v59, s41, 25
	v_writelane_b32 v59, s42, 26
	v_writelane_b32 v59, s43, 27
	v_writelane_b32 v59, s44, 28
	v_writelane_b32 v59, s45, 29
	v_writelane_b32 v59, s46, 30
	v_writelane_b32 v59, s47, 31
	v_writelane_b32 v59, s48, 32
	v_writelane_b32 v59, s49, 33
	v_writelane_b32 v59, s50, 34
	v_writelane_b32 v59, s51, 35
	v_writelane_b32 v59, s52, 36
	v_writelane_b32 v59, s53, 37
	v_writelane_b32 v59, s54, 38
	v_writelane_b32 v59, s55, 39
	s_memrealtime s[40:41]
	s_waitcnt lgkmcnt(0)
	s_add_u32 s42, s40, 1000

.Lwt8_loop:
	s_cmp_ge_u32 s16, 0x580
	s_cbranch_scc1 .Lwt8_done
	s_branch .Lwt8_d0
.Lwt8_d0:
	s_sub_u32 s19, s16, 0x0
	s_mov_b32 s46, 0x98
	s_mov_b32 s47, 0x1600000
	s_mov_b32 s48, 0x90
	s_mov_b32 s49, 0x1000
	s_mov_b32 s50, 0x4700000
	s_mov_b32 s51, 1
	s_mov_b32 s26, 0x5800
	s_mov_b32 s39, 0x160000
	s_mov_b32 s27, 0x800
	s_mov_b32 s28, 0x58
	s_mov_b32 s29, 0x2e8ba2f
	s_mov_b32 s30, 1
	s_mov_b32 s31, 0x0
	s_branch .Lwt8_common
